# attention k-loop: next k-tile's five LDS-DMA pieces issued behind the first four K-fragment reads instead of between the barrier and those reads
# speedup vs baseline: 1.0081x; 1.0081x over previous
; #define MFMA16(a, b, c) __builtin_amdgcn_mfma_f32_16x16x32_bf16((a), (b), (c), 0, 0, 0)
;     ...
;         auto issue = [&](int kt, int st) {
;             char* sb = smem + st * AT_STAGE;
; #pragma unroll
;             for (int i = 0; i < 3; ++i)
;                 __builtin_amdgcn_global_load_lds((const __attribute__((address_space(1))) void*)(P.ws + (koff[i] + (unsigned)kt * kst[i])), (__attribute__((address_space(3))) void*)(sb + (3 * w + i) * 1024), 16, 0, 0);
; #pragma unroll
;             for (int i = 0; i < 2; ++i)
;                 __builtin_amdgcn_global_load_lds((const __attribute__((address_space(1))) void*)(P.ws + (voff[i] + (unsigned)kt * 128u)), (__attribute__((address_space(3))) void*)(sb + AT_KB + (2 * w + i) * 1024), 16, 0, 0);
;         };
;         __syncthreads();
;         issue(0, 0); asm volatile("s_waitcnt vmcnt(0)" ::: "memory"); __syncthreads();
;         for (int kt = 0; kt < nkt; ++kt) {
;             const bool more = kt + 1 < nkt;
;             if (more) issue(kt + 1, (kt + 1) & 1);
;             const char* sb = smem + (kt & 1) * AT_STAGE;
;             if (kt * 64 < q1w) {
;             f32x4 as[4][2];
; #pragma unroll
;             for (int kb = 0; kb < 4; ++kb)
; #pragma unroll
;                 for (int qb = 0; qb < 2; ++qb) as[kb][qb] = (f32x4){0.f, 0.f, 0.f, 0.f};
; #pragma unroll
;             for (int ds = 0; ds < 6; ++ds) {
;                 const int ch = 4 * ds + qq;
; #pragma unroll
;                 for (int kb = 0; kb < 4; ++kb) {
;                     const int krow = krow0 + 32 * (kb >> 1) + 4 * (kb & 1), key = kkey;
;                     const bf16x8 kf = *(const bf16x8*)(sb + krow * 384 + (((ch & 24) | ((ch ^ key) & 7)) << 4));
; #pragma unroll
;                     for (int qb = 0; qb < 2; ++qb) as[kb][qb] = MFMA16(kf, qf[ds][qb], as[kb][qb]);
;                 }
;             }
.LBB0_931:
	s_add_u32 s98, s22, s90
	s_addc_u32 s99, s23, s91
	global_load_dword v251, v177, s[98:99]
	s_add_i32 s88, s0, 1
	s_bitcmp1_b32 s88, 0
	s_cselect_b32 s1, 0xa000, 0
	s_add_i32 s19, s1, 16
	v_readfirstlane_b32 s100, v186
	v_readfirstlane_b32 s101, v187
	v_cmp_lt_i32_e32 vcc, s92, v222
	s_add_i32 s100, s100, s19
	s_add_i32 s101, s101, s19
	s_and_saveexec_b64 s[26:27], vcc
	s_cbranch_execz .Lattn_skip_dma
	s_bitcmp1_b32 s0, 0
	s_cselect_b32 s1, 0xa000, 0
	s_add_i32 s93, s1, 16
	v_add3_u32 v148, s93, v198, v199
	v_add3_u32 v152, s93, v200, v199
	ds_read_b128 v[144:147], v148
	ds_read_b128 v[236:239], v148 offset:1536
	ds_read_b128 v[240:243], v148 offset:12288
	ds_read_b128 v[244:247], v148 offset:13824
	s_cmp_ge_u32 s0, s35
	s_cselect_b64 s[0:1], -1, 0
	s_and_b64 vcc, exec, s[0:1]
	v_add3_u32 v248, s93, v188, v201
	v_add3_u32 v250, s93, v188, v202
	s_mov_b32 m0, s100
	s_nop 0
	global_load_lds_dwordx4 v235, s[22:23]
	s_add_i32 m0, s100, 0x400
	s_nop 0
	global_load_lds_dwordx4 v234, s[22:23]
	s_add_i32 m0, s100, 0x800
	s_nop 0
	global_load_lds_dwordx4 v233, s[22:23]
	s_add_i32 m0, s101, 0x6000
	s_nop 0
	global_load_lds_dwordx4 v232, s[22:23]
	s_add_i32 m0, s101, 0x6400
	s_nop 0
	global_load_lds_dwordx4 v231, s[22:23]
	s_waitcnt lgkmcnt(3)
	v_mfma_f32_16x16x32_bf16 v[128:131], v[144:147], v[104:107], 0
	v_mfma_f32_16x16x32_bf16 v[116:119], v[144:147], v[108:111], 0
	ds_read_b128 v[144:147], v152
	s_waitcnt lgkmcnt(3)
	v_mfma_f32_16x16x32_bf16 v[124:127], v[236:239], v[104:107], 0
	v_mfma_f32_16x16x32_bf16 v[112:115], v[236:239], v[108:111], 0
	ds_read_b128 v[236:239], v152 offset:1536
	s_waitcnt lgkmcnt(3)
	v_mfma_f32_16x16x32_bf16 v[132:135], v[240:243], v[104:107], 0
	v_mfma_f32_16x16x32_bf16 v[120:123], v[240:243], v[108:111], 0
	ds_read_b128 v[240:243], v152 offset:12288
	s_waitcnt lgkmcnt(3)
	v_mfma_f32_16x16x32_bf16 v[140:143], v[244:247], v[104:107], 0
	v_mfma_f32_16x16x32_bf16 v[136:139], v[244:247], v[108:111], 0
	ds_read_b128 v[244:247], v152 offset:13824
	s_waitcnt lgkmcnt(3)
	v_mfma_f32_16x16x32_bf16 v[128:131], v[144:147], v[96:99], v[128:131]
	v_mfma_f32_16x16x32_bf16 v[116:119], v[144:147], v[100:103], v[116:119]
	ds_read_b128 v[144:147], v148 offset:128
	s_waitcnt lgkmcnt(3)
	v_mfma_f32_16x16x32_bf16 v[124:127], v[236:239], v[96:99], v[124:127]
	v_mfma_f32_16x16x32_bf16 v[112:115], v[236:239], v[100:103], v[112:115]
	ds_read_b128 v[236:239], v148 offset:1664
	s_waitcnt lgkmcnt(3)
	v_mfma_f32_16x16x32_bf16 v[132:135], v[240:243], v[96:99], v[132:135]
	v_mfma_f32_16x16x32_bf16 v[120:123], v[240:243], v[100:103], v[120:123]
	ds_read_b128 v[240:243], v148 offset:12416
	s_waitcnt lgkmcnt(3)
	v_mfma_f32_16x16x32_bf16 v[140:143], v[244:247], v[96:99], v[140:143]
	v_mfma_f32_16x16x32_bf16 v[136:139], v[244:247], v[100:103], v[136:139]
	ds_read_b128 v[244:247], v148 offset:13952
	s_waitcnt lgkmcnt(3)
	v_mfma_f32_16x16x32_bf16 v[128:131], v[144:147], v[88:91], v[128:131]
	v_mfma_f32_16x16x32_bf16 v[116:119], v[144:147], v[92:95], v[116:119]
	ds_read_b128 v[144:147], v152 offset:128
	s_waitcnt lgkmcnt(3)
	v_mfma_f32_16x16x32_bf16 v[124:127], v[236:239], v[88:91], v[124:127]
	v_mfma_f32_16x16x32_bf16 v[112:115], v[236:239], v[92:95], v[112:115]
	ds_read_b128 v[236:239], v152 offset:1664
	s_waitcnt lgkmcnt(3)
	v_mfma_f32_16x16x32_bf16 v[132:135], v[240:243], v[88:91], v[132:135]
	v_mfma_f32_16x16x32_bf16 v[120:123], v[240:243], v[92:95], v[120:123]
	ds_read_b128 v[240:243], v152 offset:12416
	s_waitcnt lgkmcnt(3)
	v_mfma_f32_16x16x32_bf16 v[140:143], v[244:247], v[88:91], v[140:143]
	v_mfma_f32_16x16x32_bf16 v[136:139], v[244:247], v[92:95], v[136:139]
	ds_read_b128 v[244:247], v152 offset:13952
	s_waitcnt lgkmcnt(3)
	v_mfma_f32_16x16x32_bf16 v[128:131], v[144:147], v[80:83], v[128:131]
	v_mfma_f32_16x16x32_bf16 v[116:119], v[144:147], v[84:87], v[116:119]
	ds_read_b128 v[144:147], v148 offset:256
	s_waitcnt lgkmcnt(3)
	v_mfma_f32_16x16x32_bf16 v[124:127], v[236:239], v[80:83], v[124:127]
	v_mfma_f32_16x16x32_bf16 v[112:115], v[236:239], v[84:87], v[112:115]
	ds_read_b128 v[236:239], v148 offset:1792
	s_waitcnt lgkmcnt(3)
	v_mfma_f32_16x16x32_bf16 v[132:135], v[240:243], v[80:83], v[132:135]
	v_mfma_f32_16x16x32_bf16 v[120:123], v[240:243], v[84:87], v[120:123]
	ds_read_b128 v[240:243], v148 offset:12544
	s_waitcnt lgkmcnt(3)
	v_mfma_f32_16x16x32_bf16 v[140:143], v[244:247], v[80:83], v[140:143]
	v_mfma_f32_16x16x32_bf16 v[136:139], v[244:247], v[84:87], v[136:139]
	ds_read_b128 v[244:247], v148 offset:14080
	s_waitcnt lgkmcnt(3)
	v_mfma_f32_16x16x32_bf16 v[128:131], v[144:147], v[72:75], v[128:131]
	v_mfma_f32_16x16x32_bf16 v[116:119], v[144:147], v[76:79], v[116:119]
	ds_read_b128 v[144:147], v152 offset:256
	s_waitcnt lgkmcnt(3)
	v_mfma_f32_16x16x32_bf16 v[124:127], v[236:239], v[72:75], v[124:127]
	v_mfma_f32_16x16x32_bf16 v[112:115], v[236:239], v[76:79], v[112:115]
	ds_read_b128 v[236:239], v152 offset:1792
	s_waitcnt lgkmcnt(3)
	v_mfma_f32_16x16x32_bf16 v[132:135], v[240:243], v[72:75], v[132:135]
	v_mfma_f32_16x16x32_bf16 v[120:123], v[240:243], v[76:79], v[120:123]
	ds_read_b128 v[240:243], v152 offset:12544
	s_waitcnt lgkmcnt(3)
	v_mfma_f32_16x16x32_bf16 v[140:143], v[244:247], v[72:75], v[140:143]
	v_mfma_f32_16x16x32_bf16 v[136:139], v[244:247], v[76:79], v[136:139]
	ds_read_b128 v[244:247], v152 offset:14080
	s_waitcnt lgkmcnt(3)
	v_mfma_f32_16x16x32_bf16 v[128:131], v[144:147], v[64:67], v[128:131]
	v_mfma_f32_16x16x32_bf16 v[116:119], v[144:147], v[68:71], v[116:119]
	s_waitcnt lgkmcnt(2)
	v_mfma_f32_16x16x32_bf16 v[124:127], v[236:239], v[64:67], v[124:127]
	v_mfma_f32_16x16x32_bf16 v[112:115], v[236:239], v[68:71], v[112:115]
	ds_read_b128 v[236:239], v248 offset:24576
	s_waitcnt lgkmcnt(2)
	v_mfma_f32_16x16x32_bf16 v[132:135], v[240:243], v[64:67], v[132:135]
	v_mfma_f32_16x16x32_bf16 v[120:123], v[240:243], v[68:71], v[120:123]
	ds_read_b128 v[240:243], v248 offset:26624
	s_waitcnt lgkmcnt(2)
	v_mfma_f32_16x16x32_bf16 v[140:143], v[244:247], v[64:67], v[140:143]
	v_mfma_f32_16x16x32_bf16 v[136:139], v[244:247], v[68:71], v[136:139]
	ds_read_b128 v[244:247], v248 offset:28672
	s_cbranch_vccnz .LBB0_934
	s_waitcnt vmcnt(5)
	v_cmp_gt_i32_e64 s[0:1], v251, v223
